# MLA tile loops: per-tile scalar decisions and the early waves' K-fragment address moved in front of the tile barrier (back-edge rotation), on top of the SB loop-edge edits
# speedup vs baseline: 1.0073x; 1.0073x over previous
; DI void mla_block(const Params& p, LAS unsigned char* lds, int b, int hd, int qb, int tid) {
;     ...
;     for (int kt = 0; kt < ntiles; ++kt) {
;         asm volatile("s_waitcnt vmcnt(0)" ::: "memory");
;         __builtin_amdgcn_s_barrier();
;         asm volatile("" ::: "memory");
;         const int bprev = bcur == 0 ? 2 : bcur - 1, bnext = bcur == 2 ? 0 : bcur + 1;
;         if (kt + 1 < ntiles) MLA_STAGE(kt + 1, bnext);
;         if (late && kt >= 1 && kt - 1 <= wlast) mla_pv(lds + bprev * MLA_BUF, r, h, pf0, pf1, o);
;         if (kt <= wlast) {
;             mla_s_softmax(lds + bcur * MLA_BUF, r, h, kt == wlast, q0 + r - kt * 64, qf, o, m_run, l_run, pf0, pf1);
;             if (!late) mla_pv(lds + bcur * MLA_BUF, r, h, pf0, pf1, o);
.LBB0_622:
	s_add_i32 s76, s73, 1
	s_cmp_lg_u32 s73, 2
	s_cselect_b32 s76, s76, 0
	s_add_i32 s88, s77, 1
	s_cmp_ge_u32 s88, s74
	s_cbranch_scc1 .Lmla_gen_0
	s_andn2_b64 vcc, exec, s[2:3]
	s_cbranch_vccnz .Lmla_toplate_0
	s_cmp_gt_i32 s77, s33
	s_cbranch_scc1 .Lmla_stnow_0
	s_mul_i32 s89, s73, 0xac00
	s_add_i32 s73, s89, 0
	v_add3_u32 v0, s73, v174, v162
	s_waitcnt vmcnt(0)
	s_barrier
	s_branch .Lmla_splain_0
.Lmla_toplate_0:
	s_cmp_eq_u32 s77, 0
	s_cbranch_scc1 .Lmla_stnow_0
	s_cmp_le_i32 s77, s84
	s_cbranch_scc0 .Lmla_stnow_0
.Lmla_gen_0:
	s_waitcnt vmcnt(0)
	s_barrier
	s_branch .LBB0_635
.Lmla_stnow_0:
	s_waitcnt vmcnt(0)
	s_barrier
	s_mul_i32 s89, s76, 0xac00
	s_andn2_b64 vcc, exec, s[80:81]
	s_add_i32 s89, s89, 0
	s_cbranch_vccnz .LBB0_629
	v_readlane_b32 s90, v255, 11
	v_lshl_add_u32 v0, s88, v176, v166
	s_add_i32 m0, s89, s90
	s_nop 0
	global_load_lds_dwordx4 v0, s[12:13]
	s_andn2_b64 vcc, exec, s[82:83]
	s_cbranch_vccz .LBB0_630

; DI void mla_block(const Params& p, LAS unsigned char* lds, int b, int hd, int qb, int tid) {
;     ...
;     for (int kt = 0; kt < ntiles; ++kt) {
;         asm volatile("s_waitcnt vmcnt(0)" ::: "memory");
;         __builtin_amdgcn_s_barrier();
;         asm volatile("" ::: "memory");
;         const int bprev = bcur == 0 ? 2 : bcur - 1, bnext = bcur == 2 ? 0 : bcur + 1;
;         if (kt + 1 < ntiles) MLA_STAGE(kt + 1, bnext);
;         if (late && kt >= 1 && kt - 1 <= wlast) mla_pv(lds + bprev * MLA_BUF, r, h, pf0, pf1, o);
;         if (kt <= wlast) {
;             mla_s_softmax(lds + bcur * MLA_BUF, r, h, kt == wlast, q0 + r - kt * 64, qf, o, m_run, l_run, pf0, pf1);
;             if (!late) mla_pv(lds + bcur * MLA_BUF, r, h, pf0, pf1, o);
.LBB0_724:
	s_add_i32 s76, s87, 1
	s_cmp_lg_u32 s87, 2
	s_cselect_b32 s76, s76, 0
	s_add_i32 s77, s88, 1
	s_sub_i32 s98, s73, s77
	s_sub_i32 s99, s73, s88
	s_cmp_eq_u32 s88, 0
	s_cselect_b32 s99, 0, s99
	s_cmp_eq_u32 s88, 1
	s_cselect_b32 s100, -1, s99
	s_cmp_ge_u32 s77, s73
	s_cbranch_scc1 .Lmla_gen_1
	s_andn2_b64 vcc, exec, s[2:3]
	s_cbranch_vccnz .Lmla_toplate_1
	s_cmp_gt_i32 s99, s33
	s_cbranch_scc1 .Lmla_stnow_1
	s_mul_i32 s89, s87, 0xac00
	s_add_i32 s87, s89, 0
	v_add3_u32 v0, s87, v175, v162
	s_waitcnt vmcnt(0)
	s_barrier
	s_branch .Lmla_splain_1
.Lmla_toplate_1:
	s_cmp_eq_u32 s88, 0
	s_cbranch_scc1 .Lmla_stnow_1
	s_cmp_lt_i32 s100, s33
	s_cbranch_scc0 .Lmla_stnow_1

; DI void mla_block(const Params& p, LAS unsigned char* lds, int b, int hd, int qb, int tid) {
;     ...
;         if (kt + 1 < ntiles) MLA_STAGE(kt + 1, bnext);
.Lmla_stnow_1:
	s_waitcnt vmcnt(0)
	s_barrier
	s_mul_i32 s89, s76, 0xac00
	s_andn2_b64 vcc, exec, s[80:81]
	s_add_i32 s89, s89, 0
	s_cbranch_vccnz .LBB0_731
	v_readlane_b32 s90, v255, 9
	v_lshl_add_u32 v0, s98, v176, v166
	s_add_i32 m0, s89, s90
	s_nop 0
	global_load_lds_dwordx4 v0, s[12:13]
	s_andn2_b64 vcc, exec, s[82:83]
	s_cbranch_vccz .LBB0_732
